# cache policy: final RMSNorm streaming loads and output stores also nt
# baseline (speedup 1.0000x reference)
.LBB0_1121:
	s_waitcnt lgkmcnt(0)
	v_ashrrev_i32_e32 v7, 31, v6
	v_lshlrev_b64 v[8:9], 11, v[6:7]
	v_lshl_add_u64 v[8:9], v[2:3], 0, v[8:9]
	global_load_dwordx4 v[10:13], v[8:9], off nt
	global_load_dwordx4 v[14:17], v[8:9], off offset:1024 nt
	global_load_dwordx4 v[18:21], v[0:1], off offset:16 nt
	global_load_dwordx4 v[22:25], v[0:1], off nt
	v_add_u32_e32 v33, s5, v6
	v_cmp_gt_i32_e32 vcc, s4, v33
	s_waitcnt vmcnt(0)
	v_lshlrev_b32_e32 v44, 16, v12
	v_cndmask_b32_e32 v8, v6, v33, vcc
	v_ashrrev_i32_e32 v9, 31, v8
	v_lshlrev_b64 v[34:35], 11, v[8:9]
	v_lshl_add_u64 v[42:43], v[2:3], 0, v[34:35]
	global_load_dwordx4 v[34:37], v[42:43], off nt
	global_load_dwordx4 v[38:41], v[42:43], off offset:1024 nt
	v_lshlrev_b32_e32 v42, 16, v10
	v_and_b32_e32 v43, 0xffff0000, v10
	v_lshlrev_b32_e32 v10, 16, v11
	v_and_b32_e32 v11, 0xffff0000, v11
	v_lshlrev_b32_e32 v50, 16, v14
	v_and_b32_e32 v51, 0xffff0000, v14
	v_lshlrev_b32_e32 v52, 16, v15
	v_and_b32_e32 v53, 0xffff0000, v15
	v_pk_mul_f32 v[14:15], v[42:43], v[42:43]
	v_lshlrev_b32_e32 v54, 16, v16
	v_and_b32_e32 v55, 0xffff0000, v16
	v_lshlrev_b32_e32 v56, 16, v17
	v_and_b32_e32 v57, 0xffff0000, v17
	v_pk_mul_f32 v[16:17], v[10:11], v[10:11]
	v_add_f32_e32 v14, v14, v15
	v_and_b32_e32 v45, 0xffff0000, v12
	v_add_f32_e32 v14, v14, v16
	v_pk_mul_f32 v[46:47], v[44:45], v[44:45]
	v_add_f32_e32 v14, v14, v17
	v_lshlrev_b32_e32 v12, 16, v13
	v_and_b32_e32 v13, 0xffff0000, v13
	v_add_f32_e32 v14, v14, v46
	v_pk_mul_f32 v[48:49], v[12:13], v[12:13]
	v_add_f32_e32 v14, v14, v47
	v_add_f32_e32 v14, v14, v48
	v_pk_mul_f32 v[58:59], v[50:51], v[50:51]
	v_add_f32_e32 v14, v14, v49
	v_add_f32_e32 v14, v14, v58
	v_pk_mul_f32 v[60:61], v[52:53], v[52:53]
	v_add_f32_e32 v14, v14, v59
	v_add_f32_e32 v14, v14, v60
	v_pk_mul_f32 v[62:63], v[54:55], v[54:55]
	v_add_f32_e32 v14, v14, v61
	v_add_f32_e32 v14, v14, v62
	v_pk_mul_f32 v[64:65], v[56:57], v[56:57]
	v_add_f32_e32 v14, v14, v63
	v_add_f32_e32 v14, v14, v64
	v_add_f32_e32 v14, v14, v65
	ds_bpermute_b32 v15, v26, v14
	s_waitcnt lgkmcnt(0)
	v_add_f32_e32 v14, v14, v15
	ds_bpermute_b32 v15, v27, v14
	s_waitcnt lgkmcnt(0)
	v_add_f32_e32 v14, v14, v15
	ds_bpermute_b32 v15, v28, v14
	s_waitcnt lgkmcnt(0)
	v_add_f32_e32 v14, v14, v15
	ds_bpermute_b32 v15, v29, v14
	s_waitcnt lgkmcnt(0)
	v_add_f32_e32 v14, v14, v15
	ds_bpermute_b32 v15, v30, v14
	s_waitcnt lgkmcnt(0)
	v_add_f32_e32 v14, v14, v15
	ds_bpermute_b32 v15, v31, v14
	s_waitcnt lgkmcnt(0)
	v_add_f32_e32 v14, v14, v15
	v_fmamk_f32 v14, v14, 0x3a800000, v32
	v_mul_f32_e32 v15, 0x4b800000, v14
	v_cmp_gt_f32_e32 vcc, s6, v14
	s_nop 1
	v_cndmask_b32_e32 v14, v14, v15, vcc
	v_rsq_f32_e32 v16, v14
	v_lshlrev_b64 v[14:15], 12, v[6:7]
	v_lshl_add_u64 v[58:59], v[4:5], 0, v[14:15]
	v_mul_f32_e32 v7, 0x45800000, v16
	v_cndmask_b32_e32 v60, v16, v7, vcc
	v_pk_mul_f32 v[14:15], v[60:61], v[42:43] op_sel_hi:[0,1]
	v_pk_mul_f32 v[10:11], v[60:61], v[10:11] op_sel_hi:[0,1]
	v_pk_mul_f32 v[42:43], v[60:61], v[44:45] op_sel_hi:[0,1]
	v_pk_mul_f32 v[16:17], v[60:61], v[12:13] op_sel_hi:[0,1]
	v_pk_mul_f32 v[12:13], v[24:25], v[10:11]
	v_pk_mul_f32 v[10:11], v[22:23], v[14:15]
	v_pk_mul_f32 v[16:17], v[20:21], v[16:17]
	v_pk_mul_f32 v[14:15], v[18:19], v[42:43]
	global_store_dwordx4 v[58:59], v[10:13], off nt
	global_store_dwordx4 v[58:59], v[14:17], off offset:16 nt
	global_load_dwordx4 v[42:45], v[0:1], off offset:2048 nt
	global_load_dwordx4 v[46:49], v[0:1], off offset:2064 nt
	s_waitcnt vmcnt(5)
	v_lshlrev_b32_e32 v22, 16, v34
	v_and_b32_e32 v23, 0xffff0000, v34
	v_lshlrev_b32_e32 v24, 16, v35
	v_and_b32_e32 v25, 0xffff0000, v35
	v_pk_mul_f32 v[34:35], v[22:23], v[22:23]
	v_lshlrev_b32_e32 v18, 16, v36
	v_and_b32_e32 v19, 0xffff0000, v36
	v_lshlrev_b32_e32 v20, 16, v37
	v_and_b32_e32 v21, 0xffff0000, v37
	v_pk_mul_f32 v[36:37], v[24:25], v[24:25]
	v_add_f32_e32 v7, v34, v35
	v_add_f32_e32 v7, v7, v36
	s_waitcnt vmcnt(4)
	v_lshlrev_b32_e32 v12, 16, v38
	v_and_b32_e32 v13, 0xffff0000, v38
	v_lshlrev_b32_e32 v16, 16, v39
	v_and_b32_e32 v17, 0xffff0000, v39
	v_pk_mul_f32 v[38:39], v[18:19], v[18:19]
	v_add_f32_e32 v7, v7, v37
	v_add_f32_e32 v7, v7, v38
	v_lshlrev_b32_e32 v10, 16, v40
	v_and_b32_e32 v11, 0xffff0000, v40
	v_lshlrev_b32_e32 v14, 16, v41
	v_and_b32_e32 v15, 0xffff0000, v41
	v_pk_mul_f32 v[40:41], v[20:21], v[20:21]
	v_add_f32_e32 v7, v7, v39
	v_add_f32_e32 v7, v7, v40
	v_pk_mul_f32 v[62:63], v[12:13], v[12:13]
	v_add_f32_e32 v7, v7, v41
	v_add_f32_e32 v7, v7, v62
	v_pk_mul_f32 v[64:65], v[16:17], v[16:17]
	v_add_f32_e32 v7, v7, v63
	v_add_f32_e32 v7, v7, v64
	v_pk_mul_f32 v[66:67], v[10:11], v[10:11]
	v_add_f32_e32 v7, v7, v65
	v_add_f32_e32 v7, v7, v66
	v_pk_mul_f32 v[68:69], v[14:15], v[14:15]
	v_add_f32_e32 v7, v7, v67
	v_add_f32_e32 v7, v7, v68
	v_add_f32_e32 v7, v7, v69
	ds_bpermute_b32 v34, v26, v7
	v_cmp_ne_u32_e32 vcc, v6, v8
	v_pk_mul_f32 v[36:37], v[60:61], v[52:53] op_sel_hi:[0,1]
	v_pk_mul_f32 v[40:41], v[60:61], v[56:57] op_sel_hi:[0,1]
	v_pk_mul_f32 v[38:39], v[60:61], v[54:55] op_sel_hi:[0,1]
	s_waitcnt lgkmcnt(0)
	v_add_f32_e32 v7, v7, v34
	ds_bpermute_b32 v34, v27, v7
	s_waitcnt lgkmcnt(0)
	v_add_f32_e32 v7, v7, v34
	ds_bpermute_b32 v34, v28, v7
	s_waitcnt lgkmcnt(0)
	v_add_f32_e32 v7, v7, v34
	ds_bpermute_b32 v34, v29, v7
	s_waitcnt lgkmcnt(0)
	v_add_f32_e32 v7, v7, v34
	ds_bpermute_b32 v34, v30, v7
	s_waitcnt lgkmcnt(0)
	v_add_f32_e32 v6, v7, v34
	ds_bpermute_b32 v7, v31, v6
	v_pk_mul_f32 v[34:35], v[60:61], v[50:51] op_sel_hi:[0,1]
	s_waitcnt vmcnt(1)
	v_pk_mul_f32 v[34:35], v[42:43], v[34:35]
	v_pk_mul_f32 v[36:37], v[44:45], v[36:37]
	s_waitcnt vmcnt(0)
	v_pk_mul_f32 v[38:39], v[46:47], v[38:39]
	v_pk_mul_f32 v[40:41], v[48:49], v[40:41]
	global_store_dwordx4 v[58:59], v[34:37], off offset:2048 nt
	global_store_dwordx4 v[58:59], v[38:41], off offset:2064 nt
	s_and_saveexec_b64 s[2:3], vcc
	s_cbranch_execz .LBB0_1120
	global_load_dwordx4 v[34:37], v[0:1], off nt
	global_load_dwordx4 v[38:41], v[0:1], off offset:16 nt
	s_waitcnt lgkmcnt(0)
	v_add_f32_e32 v6, v6, v7
	v_fmamk_f32 v6, v6, 0x3a800000, v32
	v_mul_f32_e32 v7, 0x4b800000, v6
	v_cmp_gt_f32_e32 vcc, s6, v6
	s_nop 1
	v_cndmask_b32_e32 v6, v6, v7, vcc
	v_rsq_f32_e32 v44, v6
	v_lshlrev_b64 v[6:7], 12, v[8:9]
	v_lshl_add_u64 v[42:43], v[4:5], 0, v[6:7]
	v_mul_f32_e32 v6, 0x45800000, v44
	v_cndmask_b32_e32 v44, v44, v6, vcc
	v_pk_mul_f32 v[6:7], v[44:45], v[22:23] op_sel_hi:[0,1]
	v_pk_mul_f32 v[8:9], v[44:45], v[24:25] op_sel_hi:[0,1]
	v_pk_mul_f32 v[18:19], v[44:45], v[18:19] op_sel_hi:[0,1]
	v_pk_mul_f32 v[20:21], v[44:45], v[20:21] op_sel_hi:[0,1]
	v_pk_mul_f32 v[16:17], v[44:45], v[16:17] op_sel_hi:[0,1]
	v_pk_mul_f32 v[12:13], v[44:45], v[12:13] op_sel_hi:[0,1]
	v_pk_mul_f32 v[14:15], v[44:45], v[14:15] op_sel_hi:[0,1]
	v_pk_mul_f32 v[10:11], v[44:45], v[10:11] op_sel_hi:[0,1]
	s_waitcnt vmcnt(1)
	v_pk_mul_f32 v[8:9], v[36:37], v[8:9]
	v_pk_mul_f32 v[6:7], v[34:35], v[6:7]
	s_waitcnt vmcnt(0)
	v_pk_mul_f32 v[20:21], v[40:41], v[20:21]
	v_pk_mul_f32 v[18:19], v[38:39], v[18:19]
	global_store_dwordx4 v[42:43], v[6:9], off nt
	global_store_dwordx4 v[42:43], v[18:21], off offset:16 nt
	global_load_dwordx4 v[6:9], v[0:1], off offset:2048 nt
	s_nop 0
	global_load_dwordx4 v[18:21], v[0:1], off offset:2064 nt
	s_waitcnt vmcnt(1)
	v_pk_mul_f32 v[6:7], v[6:7], v[12:13]
	v_pk_mul_f32 v[8:9], v[8:9], v[16:17]
	s_waitcnt vmcnt(0)
	v_pk_mul_f32 v[10:11], v[18:19], v[10:11]
	v_pk_mul_f32 v[12:13], v[20:21], v[14:15]
	global_store_dwordx4 v[42:43], v[6:9], off offset:2048 nt
	global_store_dwordx4 v[42:43], v[10:13], off offset:2064 nt
	s_branch .LBB0_1120
